# sc0 cache policy on the LDS-DMA tile loads (tiles are consumed once per CU: no L1 allocation)
# speedup vs baseline: 1.0040x; 1.0019x over previous
; #define RAW_BARRIER() do { asm volatile("s_waitcnt lgkmcnt(0)" ::: "memory"); __builtin_amdgcn_s_barrier(); asm volatile("" ::: "memory"); } while (0)
; template <int EPI>
; __device__ __forceinline__ void gemm_phase(const Params& p, const u16* __restrict__ A, int lda, const u16* __restrict__ BT, int ldb,
;                            int K, int N, u16* __restrict__ outb, int ldo, int resid_in, int boff) {
;     ...
;   for (int un = bstart; un < units; un += G) {
;     int tl = un, kbeg = 0, KT = KTALL;
;     bool part_unit = false;
;     if (un >= t_full) { const int v = un - t_full; tl = t_full + v / split; KT = KTALL / split; kbeg = (v % split) * KT; part_unit = true; }
;     int mt = tl / NT, nt = tl % NT;
;     if (EPI == EPI_RES && NT == 8 && G == 256 && !part_unit) {
;       const int rr = tl >> 8, bb = tl & 255;
;       const int xx = bb & 7, jj = bb >> 3;
;       mt = rr * 32 + xx * 4 + (jj >> 3);
;       nt = jj & 7;
;     } else if ((EPI == EPI_FF1 || EPI == EPI_SCALE) && G == 256 && (NT == 32 || NT == 16) && tl < (tiles & ~255)) {
;       const int rr = tl >> 8, bb = tl & 255;
;       const int xx = bb & 7, jj = bb >> 3;
;       if (NT == 32) { mt = rr * 8 + (xx >> 2) * 4 + (jj >> 3); nt = (xx & 3) * 8 + (jj & 7); }
;       else { mt = rr * 16 + (xx >> 1) * 4 + (jj >> 3); nt = (xx & 1) * 8 + (jj & 7); }
;     }
;     ...
;     for (int kt = 0; kt < KT; kt += 2) {
;       if (kt + 1 < KT) WRITEY(1);
;       if (kt + 3 < KT) LOADY(kt + 3);
;       COMPUTE(0);
;       RAW_BARRIER();
;       if (kt + 1 >= KT) break;
;       if (kt + 2 < KT) WRITEX(0);
;       if (kt + 4 < KT) LOADX(kt + 4);
;       COMPUTE(1);
;       RAW_BARRIER();
;     }
.Lgp_is_nop_pa:
	s_add_u32 m0, s31, s32
	s_nop 0
	global_load_lds_dwordx4 v130, s[0:1] sc0
	s_add_u32 m0, m0, 0x400
	s_nop 0
	global_load_lds_dwordx4 v131, s[0:1] sc0
	s_add_u32 m0, m0, 0x400
	s_nop 0
	global_load_lds_dwordx4 v132, s[0:1] sc0
	s_add_u32 m0, m0, 0x400
	s_nop 0
	global_load_lds_dwordx4 v133, s[0:1] sc0
	s_add_u32 m0, m0, 0x400
	s_nop 0
	global_load_lds_dwordx4 v134, s[0:1] sc0
	s_add_u32 m0, m0, 0x400
	s_nop 0
	global_load_lds_dwordx4 v135, s[0:1] sc0
	s_add_u32 m0, m0, 0x400
	s_nop 0
	global_load_lds_dwordx4 v136, s[0:1] sc0
	s_add_u32 m0, m0, 0x400
	s_nop 0
	global_load_lds_dwordx4 v137, s[0:1] sc0
	s_add_u32 m0, s31, s34
	s_nop 0
	global_load_lds_dwordx4 v138, s[2:3] sc0
	s_add_u32 m0, m0, 0x400
	s_nop 0
	global_load_lds_dwordx4 v139, s[2:3] sc0
	s_add_u32 m0, m0, 0x400
	s_nop 0
	global_load_lds_dwordx4 v140, s[2:3] sc0
	s_add_u32 m0, m0, 0x400
	s_nop 0
	global_load_lds_dwordx4 v141, s[2:3] sc0
	s_add_u32 s0, s0, 0x80
	s_addc_u32 s1, s1, 0
	s_add_u32 s2, s2, 0x80
	s_addc_u32 s3, s3, 0
	s_add_u32 s31, s31, 0xc000
	s_cmp_eq_u32 s31, 0x24000
	s_cselect_b32 s31, 0, s31
	s_sub_u32 s18, s18, 1
	s_cmp_lg_u32 s18, 0
	s_cbranch_scc1 .Lgp_is_done_pa
	s_add_u32 s5, s5, s42
	s_mov_b32 s13, s10
	s_mov_b32 s11, 0
	s_mov_b32 s18, 0
	s_cmp_ge_u32 s5, s38
	s_cbranch_scc1 .Lgp_su_done_pau
	s_mov_b32 s47, 0
	s_cmp_ge_u32 s5, s28
	s_cbranch_scc1 .Lgm_split_pau
	s_mov_b32 s8, 0
	s_mov_b32 s9, s39
	s_mov_b32 s10, 0
	s_cmp_eq_u32 s27, 0
	s_cbranch_scc1 .Lgm_plain_pau
	s_cmp_ge_u32 s5, s29
	s_cbranch_scc1 .Lgm_plain_pau
	s_cmp_ge_u32 s27, 4
	s_cbranch_scc0 .Lgm_mapped_pau
	s_and_b32 s36, s5, 0xffffff00
	s_and_b32 s37, s5, 7
	s_lshl_b32 s37, s37, 5
	s_or_b32 s36, s36, s37
	s_bfe_u32 s37, s5, 0x50003
	s_or_b32 s36, s36, s37
	s_cmp_eq_u32 s27, 5
	s_cbranch_scc1 .Lgm_panel_pau
	s_branch .Lgm_plain2_pau
